# s_setprio 3 for the s5_prompt chain items in MIX-1 (reset at the work fetch)
# speedup vs baseline: 1.0146x; 1.0146x over previous
.LBB0_445:
	s_setprio 3
	s_andn2_b64 vcc, exec, s[2:3]
	s_cbranch_vccnz .LBB0_134
	s_and_b32 s16, s31, 15
	s_lshl_b32 s2, s92, 4
	s_or_b32 s2, s2, s16
	s_ashr_i32 s3, s2, 31
	v_readlane_b32 s52, v252, 16
	s_lshl_b64 s[4:5], s[2:3], 2
	v_readlane_b32 s62, v252, 26
	v_readlane_b32 s63, v252, 27
	s_add_u32 s4, s62, s4
	v_mov_b32_e32 v42, v216
	s_addc_u32 s5, s63, s5
	global_load_dword v4, v201, s[4:5]
	v_and_b32_e32 v52, 63, v42
	v_lshl_or_b32 v0, s2, 6, v52
	v_ashrrev_i32_e32 v1, 31, v0
	v_readlane_b32 s60, v252, 24
	v_readlane_b32 s61, v252, 25
	v_lshlrev_b64 v[0:1], 2, v[0:1]
	v_readlane_b32 s58, v252, 22
	v_lshl_add_u64 v[2:3], s[60:61], 0, v[0:1]
	global_load_dword v37, v[2:3], off
	v_readlane_b32 s59, v252, 23
	s_mov_b32 s4, 0x3fb8aa3b
	v_readfirstlane_b32 s30, v42
	v_lshl_add_u64 v[0:1], s[58:59], 0, v[0:1]
	global_load_dword v36, v[0:1], off
	v_readlane_b32 s53, v252, 17
	v_readlane_b32 s54, v252, 18
	v_readlane_b32 s55, v252, 19
	v_readlane_b32 s56, v252, 20
	v_readlane_b32 s57, v252, 21
	v_readlane_b32 s64, v252, 28
	v_readlane_b32 s65, v252, 29
	v_readlane_b32 s66, v252, 30
	v_readlane_b32 s67, v252, 31
	s_waitcnt vmcnt(2)
	v_mul_f32_e32 v0, 0x3fb8aa3b, v4
	v_fma_f32 v1, v4, s4, -v0
	v_rndne_f32_e32 v2, v0
	v_fmac_f32_e32 v1, 0x32a5705f, v4
	v_sub_f32_e32 v0, v0, v2
	v_add_f32_e32 v0, v0, v1
	v_cvt_i32_f32_e32 v2, v2
	v_exp_f32_e32 v0, v0
	s_mov_b32 s4, 0xc2ce8ed0
	v_cmp_ngt_f32_e32 vcc, s4, v4
	s_mov_b32 s4, 0x42b17218
	v_ldexp_f32 v0, v0, v2
	v_cndmask_b32_e32 v0, 0, v0, vcc
	v_cmp_nlt_f32_e32 vcc, s4, v4
	s_brev_b32 s4, 18
	s_nop 0
	v_cndmask_b32_e32 v39, v233, v0, vcc
	s_waitcnt vmcnt(1)
	v_mul_f32_e32 v46, v37, v39
	v_and_b32_e32 v38, 0x7fffffff, v46
	v_lshrrev_b32_e32 v0, 23, v38
	v_and_b32_e32 v2, 0x7fffff, v38
	v_cmp_nlt_f32_e64 s[4:5], |v46|, s4
	v_add_u32_e32 v1, 0xffffff88, v0
	v_or_b32_e32 v0, 0x800000, v2
	s_and_saveexec_b64 s[8:9], s[4:5]
	s_xor_b64 s[14:15], exec, s[8:9]
	s_cbranch_execz .LBB0_448
	v_cmp_lt_u32_e32 vcc, 63, v1
	s_mov_b32 s12, 0xfe5163ab
	s_nop 0
	v_cndmask_b32_e32 v2, 0, v234, vcc
	v_add_u32_e32 v2, v2, v1
	v_cmp_lt_u32_e64 s[8:9], 31, v2
	s_nop 1
	v_cndmask_b32_e64 v3, 0, v235, s[8:9]
	v_add_u32_e32 v2, v3, v2
	v_cmp_lt_u32_e64 s[10:11], 31, v2
	s_nop 1
	v_cndmask_b32_e64 v3, 0, v235, s[10:11]
	v_add_u32_e32 v16, v3, v2
	v_mad_u64_u32 v[2:3], s[12:13], v0, s12, 0
	v_mov_b32_e32 v200, v3
	s_mov_b32 s12, 0x3c439041
	v_mad_u64_u32 v[4:5], s[12:13], v0, s12, v[200:201]
	v_mov_b32_e32 v200, v5
	s_mov_b32 s12, 0xdb629599
	v_mad_u64_u32 v[6:7], s[12:13], v0, s12, v[200:201]
	v_mov_b32_e32 v200, v7
	s_mov_b32 s12, 0xf534ddc0
	v_mad_u64_u32 v[8:9], s[12:13], v0, s12, v[200:201]
	v_mov_b32_e32 v200, v9
	s_mov_b32 s12, 0xfc2757d1
	v_mad_u64_u32 v[10:11], s[12:13], v0, s12, v[200:201]
	v_mov_b32_e32 v200, v11
	s_mov_b32 s12, 0x4e441529
	v_mad_u64_u32 v[12:13], s[12:13], v0, s12, v[200:201]
	v_mov_b32_e32 v200, v13
	s_mov_b32 s12, 0xa2f9836e
	v_mad_u64_u32 v[14:15], s[12:13], v0, s12, v[200:201]
	v_cndmask_b32_e32 v3, v12, v8, vcc
	v_cndmask_b32_e32 v5, v14, v10, vcc
	v_cndmask_b32_e32 v9, v15, v12, vcc
	v_cndmask_b32_e64 v7, v5, v3, s[8:9]
	v_cndmask_b32_e64 v5, v9, v5, s[8:9]
	v_cndmask_b32_e32 v9, v10, v6, vcc
	v_cndmask_b32_e64 v3, v3, v9, s[8:9]
	v_cndmask_b32_e32 v4, v8, v4, vcc
	v_cndmask_b32_e64 v5, v5, v7, s[10:11]
	v_cndmask_b32_e64 v7, v7, v3, s[10:11]
	v_sub_u32_e32 v10, 32, v16
	v_cndmask_b32_e64 v8, v9, v4, s[8:9]
	v_alignbit_b32 v11, v5, v7, v10
	v_cmp_eq_u32_e64 s[12:13], 0, v16
	v_cndmask_b32_e64 v3, v3, v8, s[10:11]
	v_alignbit_b32 v9, v7, v3, v10
	v_cndmask_b32_e64 v5, v11, v5, s[12:13]
	v_cndmask_b32_e32 v2, v6, v2, vcc
	v_cndmask_b32_e64 v7, v9, v7, s[12:13]
	v_bfe_u32 v12, v5, 29, 1
	v_cndmask_b32_e64 v2, v4, v2, s[8:9]
	v_alignbit_b32 v9, v5, v7, 30
	v_sub_u32_e32 v13, 0, v12
	v_cndmask_b32_e64 v2, v8, v2, s[10:11]
	v_xor_b32_e32 v9, v9, v13
	v_alignbit_b32 v4, v3, v2, v10
	v_cndmask_b32_e64 v3, v4, v3, s[12:13]
	v_ffbh_u32_e32 v6, v9
	v_alignbit_b32 v4, v7, v3, 30
	v_min_u32_e32 v6, 32, v6
	v_alignbit_b32 v2, v3, v2, 30
	v_xor_b32_e32 v4, v4, v13
	v_sub_u32_e32 v7, 31, v6
	v_xor_b32_e32 v2, v2, v13
	v_alignbit_b32 v8, v9, v4, v7
	v_alignbit_b32 v2, v4, v2, v7
	v_alignbit_b32 v3, v8, v2, 9
	v_ffbh_u32_e32 v4, v3
	v_min_u32_e32 v4, 32, v4
	v_lshrrev_b32_e32 v11, 29, v5
	v_not_b32_e32 v7, v4
	v_alignbit_b32 v2, v3, v2, v7
	v_lshlrev_b32_e32 v3, 31, v11
	v_or_b32_e32 v7, 0x33000000, v3
	v_add_lshl_u32 v4, v4, v6, 23
	v_lshrrev_b32_e32 v2, 9, v2
	v_sub_u32_e32 v4, v7, v4
	v_or_b32_e32 v3, 0.5, v3
	v_lshlrev_b32_e32 v6, 23, v6
	v_or_b32_e32 v2, v4, v2
	v_lshrrev_b32_e32 v4, 9, v8
	v_sub_u32_e32 v3, v3, v6
	v_or_b32_e32 v3, v4, v3
	v_mul_f32_e32 v4, 0x3fc90fda, v3
	s_mov_b32 s8, 0x3fc90fda
	v_fma_f32 v6, v3, s8, -v4
	v_fmac_f32_e32 v6, 0x33a22168, v3
	v_fmac_f32_e32 v6, 0x3fc90fda, v2
	v_lshrrev_b32_e32 v2, 30, v5
	v_add_f32_e32 v41, v4, v6
	v_add_u32_e32 v40, v12, v2
